# G4->G5 waits only for its own token-tile group plus the groups whose H rows its K/V/Q rows overwrite; pre->scan per-head 4-workgroup groups; multi-condition seams poll all their words in one loop
# baseline (speedup 1.0000x reference)
.LBB0_164:
	s_waitcnt vmcnt(0)
	v_readfirstlane_b32 s0, v194
	s_cmp_gt_u32 s0, 63
	s_waitcnt vmcnt(0)
	s_barrier
	s_cbranch_scc1 .LBB0_218
	v_mbcnt_lo_u32_b32 v0, -1, 0
	v_mbcnt_hi_u32_b32 v0, -1, v0
	s_nop 0
	v_cmp_eq_u32_e32 vcc, 0, v0
	s_and_saveexec_b64 s[0:1], vcc
	s_cbranch_execz .LBB0_217
	v_mov_b32_e32 v0, 0x23ff0
	s_waitcnt vmcnt(0) lgkmcnt(0)
	ds_read_b128 v[0:3], v0
	s_waitcnt lgkmcnt(0)
	v_readfirstlane_b32 s3, v2
	s_nop 0
	s_cmp_eq_u32 s3, 0
	s_cbranch_scc1 .Lfb_slow_0
	v_readfirstlane_b32 s8, v0
	s_cmp_eq_u32 s8, 32
	s_cbranch_scc0 .Lfb_xcd_0
	buffer_inv sc1
	s_getreg_b32 s3, hwreg(HW_REG_XCC_ID, 0, 4)
	s_and_b32 s3, s3, 7
	s_lshl_b32 s3, s3, 8
	s_add_u32 s3, s3, 0x3600
	s_add_u32 s4, s92, 0x510000
	s_addc_u32 s5, s93, 0
	v_mov_b32_e32 v7, 1
	s_bfe_u32 s8, s2, 0x20006
	s_lshl_b32 s8, s8, 2
	s_add_u32 s8, s8, s3
	s_add_u32 s8, s8, 0xe0
	v_mov_b32_e32 v6, s8
	global_atomic_add v6, v7, s[4:5]
	s_bfe_u32 s8, s2, 0x20006
	s_lshl_b32 s8, s8, 2
	s_add_u32 s8, s8, s3
	s_add_u32 s8, s8, 0xe0
	v_mov_b32_e32 v6, s8
	s_mov_b32 s8, 0
.Lfb_gs_0:
	global_load_dword v8, v6, s[4:5] sc1
	s_waitcnt vmcnt(0)
	v_add_u32_e32 v8, -8, v8
	v_cmp_le_i32_e32 vcc, 0, v8
	s_cbranch_vccnz .Lfb_done_0
	s_sleep 1
	s_add_u32 s8, s8, 1
	s_cmp_lt_u32 s8, 0x40000
	s_cbranch_scc1 .Lfb_gs_0
	s_branch .Lfb_done_0

.LBB0_308:
	s_waitcnt vmcnt(0)
	v_readfirstlane_b32 s4, v194
	s_cmp_gt_u32 s4, 63
	v_readlane_b32 s77, v242, 9
	v_readlane_b32 s78, v241, 13
	v_readlane_b32 s40, v241, 12
	v_readlane_b32 s41, v241, 4
	s_barrier
	s_cbranch_scc1 .LBB0_362
	v_mbcnt_lo_u32_b32 v0, -1, 0
	v_mbcnt_hi_u32_b32 v0, -1, v0
	s_nop 0
	v_cmp_eq_u32_e32 vcc, 0, v0
	s_and_saveexec_b64 s[6:7], vcc
	s_cbranch_execz .LBB0_361
	v_mov_b32_e32 v0, 0x23ff0
	s_waitcnt vmcnt(0) lgkmcnt(0)
	ds_read_b128 v[0:3], v0
	s_waitcnt lgkmcnt(0)
	v_readfirstlane_b32 s8, v2
	s_nop 0
	s_cmp_eq_u32 s8, 0
	s_cbranch_scc1 .Lfb_slow_1
	v_readfirstlane_b32 s9, v0
	s_cmp_eq_u32 s9, 32
	s_cbranch_scc0 .Lfb_xcd_1
	buffer_inv sc1
	s_getreg_b32 s8, hwreg(HW_REG_XCC_ID, 0, 4)
	s_and_b32 s8, s8, 7
	s_lshl_b32 s8, s8, 8
	s_add_u32 s8, s8, 0x3600
	s_add_u32 s4, s92, 0x510000
	s_addc_u32 s5, s93, 0
	v_mov_b32_e32 v7, 1
	s_bfe_u32 s9, s2, 0x30005
	s_lshl_b32 s9, s9, 2
	s_add_u32 s9, s9, s8
	s_add_u32 s9, s9, 0x60
	v_mov_b32_e32 v6, s9
	global_atomic_add v6, v7, s[4:5]
	s_bfe_u32 s9, s2, 0x30005
	s_lshl_b32 s9, s9, 2
	s_add_u32 s9, s9, s8
	s_add_u32 s9, s9, 0x60
	v_mov_b32_e32 v6, s9
	s_mov_b32 s9, 0
.Lfb_gs_1:
	global_load_dword v8, v6, s[4:5] sc1
	s_waitcnt vmcnt(0)
	v_add_u32_e32 v8, -4, v8
	v_cmp_le_i32_e32 vcc, 0, v8
	s_cbranch_vccnz .Lfb_done_1
	s_sleep 1
	s_add_u32 s9, s9, 1
	s_cmp_lt_u32 s9, 0x40000
	s_cbranch_scc1 .Lfb_gs_1
	s_branch .Lfb_done_1

.LBB0_689:
	s_waitcnt vmcnt(0)
	v_readfirstlane_b32 s3, v194
	s_cmp_gt_u32 s3, 63
	s_waitcnt lgkmcnt(0)
	s_barrier
	s_cbranch_scc1 .LBB0_743
	v_mbcnt_lo_u32_b32 v0, -1, 0
	v_mbcnt_hi_u32_b32 v0, -1, v0
	s_nop 0
	v_cmp_eq_u32_e32 vcc, 0, v0
	s_and_saveexec_b64 s[6:7], vcc
	s_cbranch_execz .LBB0_742
	v_mov_b32_e32 v20, 0x23ff0
	s_waitcnt vmcnt(0) lgkmcnt(0)
	ds_read_b128 v[20:23], v20
	s_waitcnt lgkmcnt(0)
	v_readfirstlane_b32 s3, v22
	s_nop 0
	s_cmp_eq_u32 s3, 0
	s_cbranch_scc1 .Lfb_slow_2
	v_readfirstlane_b32 s8, v20
	s_cmp_eq_u32 s8, 32
	s_cbranch_scc0 .Lfb_xcd_2
	buffer_inv sc1
	s_getreg_b32 s3, hwreg(HW_REG_XCC_ID, 0, 4)
	s_and_b32 s3, s3, 7
	s_lshl_b32 s3, s3, 8
	s_add_u32 s3, s3, 0x3600
	s_add_u32 s4, s92, 0x510000
	s_addc_u32 s5, s93, 0
	v_mov_b32_e32 v27, 1
	s_bfe_u32 s8, s2, 0x30003
	s_lshl_b32 s8, s8, 2
	s_add_u32 s8, s8, s3
	s_add_u32 s8, s8, 0xc0
	v_mov_b32_e32 v26, s8
	global_atomic_add v26, v27, s[4:5]
	s_bfe_u32 s8, s2, 0x30003
	s_lshl_b32 s8, s8, 2
	s_add_u32 s8, s8, s3
	s_add_u32 s8, s8, 0xc0
	v_mov_b32_e32 v26, s8
	s_mov_b32 s8, 0
.Lfb_gs_2:
	global_load_dword v28, v26, s[4:5] sc1
	s_waitcnt vmcnt(0)
	v_add_u32_e32 v28, -4, v28
	v_cmp_le_i32_e32 vcc, 0, v28
	s_cbranch_vccnz .Lfb_done_2
	s_sleep 1
	s_add_u32 s8, s8, 1
	s_cmp_lt_u32 s8, 0x40000
	s_cbranch_scc1 .Lfb_gs_2
	s_branch .Lfb_done_2

.LBB0_772:
	s_waitcnt vmcnt(0)
	v_readfirstlane_b32 s0, v194
	s_cmp_gt_u32 s0, 63
	s_waitcnt vmcnt(0)
	s_barrier
	s_cbranch_scc1 .LBB0_826
	v_mbcnt_lo_u32_b32 v0, -1, 0
	v_mbcnt_hi_u32_b32 v0, -1, v0
	s_nop 0
	v_cmp_eq_u32_e32 vcc, 0, v0
	s_and_saveexec_b64 s[0:1], vcc
	s_cbranch_execz .LBB0_825
	v_mov_b32_e32 v20, 0x23ff0
	s_waitcnt vmcnt(0) lgkmcnt(0)
	ds_read_b128 v[20:23], v20
	s_waitcnt lgkmcnt(0)
	v_readfirstlane_b32 s3, v22
	s_nop 0
	s_cmp_eq_u32 s3, 0
	s_cbranch_scc1 .Lfb_slow_3
	v_readfirstlane_b32 s8, v20
	s_cmp_eq_u32 s8, 32
	s_cbranch_scc0 .Lfb_xcd_3
	buffer_inv sc1
	s_getreg_b32 s3, hwreg(HW_REG_XCC_ID, 0, 4)
	s_and_b32 s3, s3, 7
	s_lshl_b32 s3, s3, 8
	s_add_u32 s3, s3, 0x3600
	s_add_u32 s4, s92, 0x510000
	s_addc_u32 s5, s93, 0
	v_mov_b32_e32 v27, 1
	s_bfe_u32 s8, s2, 0x30003
	s_lshl_b32 s8, s8, 2
	s_add_u32 s8, s8, s3
	s_add_u32 s8, s8, 0xc0
	v_mov_b32_e32 v26, s8
	global_atomic_add v26, v27, s[4:5]
	s_bfe_u32 s8, s2, 0x30003
	s_lshl_b32 s8, s8, 2
	s_add_u32 s8, s8, s3
	s_add_u32 s8, s8, 0xc0
	v_mov_b32_e32 v26, s8
	s_mov_b32 s8, 0
.Lfb_gs_3:
	global_load_dword v28, v26, s[4:5] sc1
	s_waitcnt vmcnt(0)
	v_add_u32_e32 v28, -8, v28
	v_cmp_le_i32_e32 vcc, 0, v28
	s_cbranch_vccnz .Lfb_done_3
	s_sleep 1
	s_add_u32 s8, s8, 1
	s_cmp_lt_u32 s8, 0x40000
	s_cbranch_scc1 .Lfb_gs_3
	s_branch .Lfb_done_3

.LBB0_864:
	s_waitcnt vmcnt(0)
	v_readfirstlane_b32 s3, v194
	s_cmp_gt_u32 s3, 63
	s_waitcnt lgkmcnt(0)
	s_barrier
	s_cbranch_scc1 .LBB0_918
	v_mbcnt_lo_u32_b32 v0, -1, 0
	v_mbcnt_hi_u32_b32 v0, -1, v0
	s_nop 0
	v_cmp_eq_u32_e32 vcc, 0, v0
	s_and_saveexec_b64 s[6:7], vcc
	s_cbranch_execz .LBB0_917
	v_mov_b32_e32 v20, 0x23ff0
	s_waitcnt vmcnt(0) lgkmcnt(0)
	ds_read_b128 v[20:23], v20
	s_waitcnt lgkmcnt(0)
	v_readfirstlane_b32 s3, v22
	s_nop 0
	s_cmp_eq_u32 s3, 0
	s_cbranch_scc1 .Lfb_slow_4
	v_readfirstlane_b32 s8, v20
	s_cmp_eq_u32 s8, 32
	s_cbranch_scc0 .Lfb_xcd_4
	buffer_inv sc1
	s_getreg_b32 s3, hwreg(HW_REG_XCC_ID, 0, 4)
	s_and_b32 s3, s3, 7
	s_lshl_b32 s3, s3, 8
	s_add_u32 s3, s3, 0x3600
	s_add_u32 s4, s92, 0x510000
	s_addc_u32 s5, s93, 0
	v_mov_b32_e32 v27, 1
	s_bfe_u32 s8, s2, 0x30003
	s_lshl_b32 s8, s8, 2
	s_add_u32 s8, s8, s3
	s_add_u32 s8, s8, 0xc0
	v_mov_b32_e32 v26, s8
	global_atomic_add v26, v27, s[4:5]
	s_mov_b32 s8, s3
	s_add_u32 s8, s8, 0x58
	v_mov_b32_e32 v26, s8
	global_atomic_add v26, v27, s[4:5]
	s_bfe_u32 s8, s2, 0x30003
	s_lshl_b32 s8, s8, 2
	s_add_u32 s8, s8, s3
	s_add_u32 s8, s8, 0xc0
	v_mov_b32_e32 v26, s8
	s_bfe_u32 s8, s2, 0x30003
	s_mul_i32 s8, s8, 3
	s_lshr_b32 s8, s8, 2
	s_lshl_b32 s8, s8, 2
	s_add_u32 s8, s8, s3
	s_add_u32 s8, s8, 0xc0
	v_mov_b32_e32 v24, s8
	s_bfe_u32 s8, s2, 0x30003
	s_mul_i32 s8, s8, 3
	s_add_u32 s8, s8, 2
	s_lshr_b32 s8, s8, 2
	s_lshl_b32 s8, s8, 2
	s_add_u32 s8, s8, s3
	s_add_u32 s8, s8, 0xc0
	v_mov_b32_e32 v23, s8
	s_mov_b32 s8, 0
.Lfb_gs_4:
	global_load_dword v28, v26, s[4:5] sc1
	global_load_dword v25, v24, s[4:5] sc1
	global_load_dword v22, v23, s[4:5] sc1
	s_waitcnt vmcnt(0)
	v_add_u32_e32 v28, -12, v28
	v_add_u32_e32 v25, -12, v25
	v_add_u32_e32 v22, -12, v22
	v_min_i32_e32 v28, v28, v25
	v_min_i32_e32 v28, v28, v22
	v_cmp_le_i32_e32 vcc, 0, v28
	s_cbranch_vccnz .Lfb_done_4
	s_sleep 1
	s_add_u32 s8, s8, 1
	s_cmp_lt_u32 s8, 0x40000
	s_cbranch_scc1 .Lfb_gs_4
	s_branch .Lfb_done_4

.LBB0_949:
	s_waitcnt vmcnt(0)
	v_readfirstlane_b32 s0, v194
	s_cmp_gt_u32 s0, 63
	s_waitcnt vmcnt(0)
	s_barrier
	s_cbranch_scc1 .LBB0_1003
	v_mbcnt_lo_u32_b32 v0, -1, 0
	v_mbcnt_hi_u32_b32 v0, -1, v0
	s_nop 0
	v_cmp_eq_u32_e32 vcc, 0, v0
	s_and_saveexec_b64 s[0:1], vcc
	s_cbranch_execz .LBB0_1002
	v_mov_b32_e32 v20, 0x23ff0
	s_waitcnt vmcnt(0) lgkmcnt(0)
	ds_read_b128 v[20:23], v20
	s_waitcnt lgkmcnt(0)
	v_readfirstlane_b32 s3, v22
	s_nop 0
	s_cmp_eq_u32 s3, 0
	s_cbranch_scc1 .Lfb_slow_5
	v_readfirstlane_b32 s8, v20
	s_cmp_eq_u32 s8, 32
	s_cbranch_scc0 .Lfb_xcd_5
	buffer_inv sc1
	s_getreg_b32 s3, hwreg(HW_REG_XCC_ID, 0, 4)
	s_and_b32 s3, s3, 7
	s_lshl_b32 s3, s3, 8
	s_add_u32 s3, s3, 0x3600
	s_add_u32 s4, s92, 0x510000
	s_addc_u32 s5, s93, 0
	v_mov_b32_e32 v27, 1
	s_bfe_u32 s8, s2, 0x20006
	s_lshl_b32 s8, s8, 2
	s_add_u32 s8, s8, s3
	s_add_u32 s8, s8, 0xe0
	v_mov_b32_e32 v26, s8
	global_atomic_add v26, v27, s[4:5]
	s_bfe_u32 s8, s2, 0x20006
	s_lshl_b32 s8, s8, 2
	s_add_u32 s8, s8, s3
	s_add_u32 s8, s8, 0xe0
	v_mov_b32_e32 v26, s8
	s_mov_b32 s8, s3
	s_add_u32 s8, s8, 0x58
	v_mov_b32_e32 v24, s8
	s_mov_b32 s8, 0
.Lfb_gs_5:
	global_load_dword v28, v26, s[4:5] sc1
	global_load_dword v25, v24, s[4:5] sc1
	s_waitcnt vmcnt(0)
	v_add_u32_e32 v28, -16, v28
	v_add_u32_e32 v25, -32, v25
	v_min_i32_e32 v28, v28, v25
	v_cmp_le_i32_e32 vcc, 0, v28
	s_cbranch_vccnz .Lfb_done_5
	s_sleep 1
	s_add_u32 s8, s8, 1
	s_cmp_lt_u32 s8, 0x40000
	s_cbranch_scc1 .Lfb_gs_5
	s_branch .Lfb_done_5

.Lfb_aw_6:
	s_lshl_b32 s8, s8, 2
	s_add_u32 s8, s8, s3
	s_add_u32 s8, s8, 0x40
	v_mov_b32_e32 v26, s8
	s_mov_b32 s8, 0

.LBB0_1249:
	s_waitcnt vmcnt(0)
	v_readfirstlane_b32 s3, v194
	s_cmp_gt_u32 s3, 63
	s_waitcnt lgkmcnt(0)
	s_barrier
	s_cbranch_scc1 .LBB0_1303
	v_mbcnt_lo_u32_b32 v0, -1, 0
	v_mbcnt_hi_u32_b32 v0, -1, v0
	s_nop 0
	v_cmp_eq_u32_e32 vcc, 0, v0
	s_and_saveexec_b64 s[6:7], vcc
	s_cbranch_execz .LBB0_1302
	v_mov_b32_e32 v20, 0x23ff0
	s_waitcnt vmcnt(0) lgkmcnt(0)
	ds_read_b128 v[20:23], v20
	s_waitcnt lgkmcnt(0)
	v_readfirstlane_b32 s3, v22
	s_nop 0
	s_cmp_eq_u32 s3, 0
	s_cbranch_scc1 .Lfb_slow_7
	v_readfirstlane_b32 s8, v20
	s_cmp_eq_u32 s8, 32
	s_cbranch_scc0 .Lfb_xcd_7
	buffer_inv sc1
	s_getreg_b32 s3, hwreg(HW_REG_XCC_ID, 0, 4)
	s_and_b32 s3, s3, 7
	s_lshl_b32 s3, s3, 8
	s_add_u32 s3, s3, 0x3600
	s_add_u32 s4, s92, 0x510000
	s_addc_u32 s5, s93, 0
	v_mov_b32_e32 v27, 1
	s_bfe_u32 s8, s2, 0x30003
	s_lshl_b32 s8, s8, 2
	s_add_u32 s8, s8, s3
	s_add_u32 s8, s8, 0xc0
	v_mov_b32_e32 v26, s8
	global_atomic_add v26, v27, s[4:5]
	s_mov_b32 s8, s3
	s_add_u32 s8, s8, 0x54
	v_mov_b32_e32 v26, s8
	global_atomic_add v26, v27, s[4:5]
	s_bfe_u32 s8, s2, 0x30003
	s_lshl_b32 s8, s8, 2
	s_add_u32 s8, s8, s3
	s_add_u32 s8, s8, 0xc0
	v_mov_b32_e32 v26, s8
	s_mov_b32 s8, s3
	s_add_u32 s8, s8, 0x50
	v_mov_b32_e32 v24, s8
	s_mov_b32 s8, 0

.LBB0_1332:
	s_waitcnt vmcnt(0)
	v_readfirstlane_b32 s0, v194
	s_cmp_gt_u32 s0, 63
	s_waitcnt vmcnt(0)
	s_barrier
	s_cbranch_scc1 .LBB0_1386
	v_mbcnt_lo_u32_b32 v0, -1, 0
	v_mbcnt_hi_u32_b32 v0, -1, v0
	s_nop 0
	v_cmp_eq_u32_e32 vcc, 0, v0
	s_and_saveexec_b64 s[0:1], vcc
	s_cbranch_execz .LBB0_1385
	v_mov_b32_e32 v20, 0x23ff0
	s_waitcnt vmcnt(0) lgkmcnt(0)
	ds_read_b128 v[20:23], v20
	s_waitcnt lgkmcnt(0)
	v_readfirstlane_b32 s3, v22
	s_nop 0
	s_cmp_eq_u32 s3, 0
	s_cbranch_scc1 .Lfb_slow_8
	v_readfirstlane_b32 s8, v20
	s_cmp_eq_u32 s8, 32
	s_cbranch_scc0 .Lfb_xcd_8
	buffer_inv sc1
	s_getreg_b32 s3, hwreg(HW_REG_XCC_ID, 0, 4)
	s_and_b32 s3, s3, 7
	s_lshl_b32 s3, s3, 8
	s_add_u32 s3, s3, 0x3600
	s_add_u32 s4, s92, 0x510000
	s_addc_u32 s5, s93, 0
	v_mov_b32_e32 v27, 1
	s_bfe_u32 s8, s2, 0x30003
	s_lshl_b32 s8, s8, 2
	s_add_u32 s8, s8, s3
	s_add_u32 s8, s8, 0xc0
	v_mov_b32_e32 v26, s8
	global_atomic_add v26, v27, s[4:5]
	s_bfe_u32 s8, s2, 0x30003
	s_lshl_b32 s8, s8, 2
	s_add_u32 s8, s8, s3
	s_add_u32 s8, s8, 0xc0
	v_mov_b32_e32 v26, s8
	s_mov_b32 s8, s3
	s_add_u32 s8, s8, 0x54
	v_mov_b32_e32 v24, s8
	s_mov_b32 s8, 0
.Lfb_gs_8:
	global_load_dword v28, v26, s[4:5] sc1
	global_load_dword v25, v24, s[4:5] sc1
	s_waitcnt vmcnt(0)
	v_add_u32_e32 v28, -20, v28
	v_add_u32_e32 v25, -32, v25
	v_min_i32_e32 v28, v28, v25
	v_cmp_le_i32_e32 vcc, 0, v28
	s_cbranch_vccnz .Lfb_done_8
	s_sleep 1
	s_add_u32 s8, s8, 1
	s_cmp_lt_u32 s8, 0x40000
	s_cbranch_scc1 .Lfb_gs_8
	s_branch .Lfb_done_8
